# up-gemm-kloop-a-stages-moved-to-read-free-phases
# speedup vs baseline: 1.0053x; 1.0053x over previous
; #define PG8_STAGE(bufoff, gbase, hoff, imm) do { _Pragma("unroll") for (int _i = 0; _i < 2; ++_i) { \
;         asm volatile("s_mov_b32 m0, %0\n\ts_nop 0\n\tglobal_load_lds_dwordx4 %1, %2" \
;             :: "s"(lds0 + (unsigned)((bufoff) + _i * 8192)), "v"(voff0), "s"((const char*)(gbase) + (size_t)(hoff) + (size_t)(_i * 8192)) : "memory"); } } while (0)
; #define PG8_WAIT_V(n) asm volatile("s_waitcnt vmcnt(" #n ")" ::: "memory")
; #define PG8_BAR __builtin_amdgcn_s_barrier()
; template <class Epi>
; __device__ __forceinline__ void gemm_phase(LAS unsigned char* lds, const Gemm g, const StaticOrder& S, const Epi& E) {
;     ...
;     const int wid = __builtin_amdgcn_readfirstlane(tid >> 6), lane = tid & 63, wr = wid >> 2, wc = wid & 3, fr = lane & 15, fq = lane >> 4;
;     const int K = g.K, nt = K / BK;
;     const unsigned voff0 = (unsigned)(tid * 16);
;     const unsigned hA = (unsigned)(g.lda * 256), hB = (unsigned)(K * 256);
;     constexpr int KS = 16384;
;     const size_t tstepA = (size_t)BM * g.lda * 2, tstepB = (size_t)BM * K * 2;
;     const unsigned lds0 = (unsigned)__builtin_amdgcn_readfirstlane((int)((unsigned)(size_t)lds + (unsigned)wid * 1024u));
;     const int aoff = lds_byte(wr * 64 + fr, fq * 8), boff = lds_byte(wc * 32 + fr, fq * 8);
;     ...
;     const char* cA = (const char*)g.A + (size_t)cur.pm * tstepA + (size_t)(cur.pn >> g.gshift) * g.gstride; const char* cB = (const char*)g.Bt + (size_t)cur.pn * tstepB;
;     PG8_STAGE(PG8_SB(0, 0), cB, 0, 0); PG8_STAGE(PG8_SA(0, 0), cA, 0, 0); PG8_STAGE(PG8_SB(0, 1), cB, hB, 0); PG8_STAGE(PG8_SA(0, 1), cA, hA, 0);
;     if (wr == 1) PG8_BAR;
;     PG8_WAIT_V(4); PG8_BAR;
;     PG8_STAGE(PG8_SB(1, 0), cB + KS, 0, 0); PG8_STAGE(PG8_SA(1, 0), cA + KS, 0, 0); PG8_STAGE(PG8_SB(1, 1), cB + KS, hB, 0);
;     PG8_WAIT_V(6); PG8_BAR;
.LBB0_733:
	s_add_u32 s30, s4, s88
	v_readlane_b32 s4, v255, 43
	s_addc_u32 s48, s5, 0
	s_mul_i32 s4, s4, 0xb000
	s_add_u32 s6, s6, s4
	s_addc_u32 s7, s7, 0
	s_add_u32 s52, s8, 0x12630000
	s_addc_u32 s53, s9, 0
	s_add_u32 s54, s8, 0x28630000
	s_addc_u32 s55, s9, 0
	s_add_u32 s56, s8, 0x29130000
	v_and_b32_e32 v1, 63, v0
	v_and_b32_e32 v153, 15, v0
	v_lshrrev_b32_e32 v2, 1, v0
	v_and_b32_e32 v154, 48, v0
	v_lshlrev_b32_e32 v0, 2, v0
	s_addc_u32 s57, s9, 0
	s_and_b32 s8, s0, 3
	s_lshl_b32 s4, s10, 13
	v_lshl_or_b32 v3, v153, 6, v154
	v_and_b32_e32 v0, 32, v0
	s_lshl_b32 s21, s10, 6
	s_waitcnt vmcnt(0)
	v_bitop3_b32 v4, v3, s4, v0 bitop3:0xde
	s_lshl_b32 s4, s8, 12
	s_add_i32 s16, s89, 0x18000
	v_bitop3_b32 v0, v3, s4, v0 bitop3:0xde
	s_add_u32 s4, s78, 0x4000
	s_addc_u32 s5, s79, 0
	s_add_i32 s17, s89, 0x1a000
	s_waitcnt vmcnt(4)
	s_barrier
	s_mov_b32 m0, s16
	s_nop 0
	global_load_lds_dwordx4 v152, s[4:5]
	s_add_u32 s4, s78, 0x6000
	s_addc_u32 s5, s79, 0
	s_add_i32 s24, s89, 0x8000
	s_mov_b32 m0, s17
	s_nop 0
	global_load_lds_dwordx4 v152, s[4:5]
	s_add_u32 s4, s76, 0x4000
	s_addc_u32 s5, s77, 0
	s_add_i32 s37, s89, 0xa000
	s_mov_b32 m0, s24
	s_nop 0
	global_load_lds_dwordx4 v152, s[4:5]
	s_add_u32 s4, s76, 0x6000
	s_addc_u32 s5, s77, 0
	s_add_i32 s97, s89, 0x1c000
	s_mov_b32 m0, s37
	s_nop 0
	global_load_lds_dwordx4 v152, s[4:5]
	s_add_u32 s4, s78, 0x84000
	s_addc_u32 s5, s79, 0
	s_add_i32 s38, s89, 0x1e000
	s_mov_b32 m0, s97
	s_nop 0
	global_load_lds_dwordx4 v152, s[4:5]
	s_add_u32 s4, s78, 0x86000
	s_addc_u32 s5, s79, 0
	s_cmp_lt_i32 s0, 4
	v_readlane_b32 s49, v255, 38
	s_mov_b32 m0, s38
	s_nop 0
	global_load_lds_dwordx4 v152, s[4:5]
	s_cselect_b64 s[58:59], -1, 0
	s_add_i32 s4, s49, s11
	s_add_i32 s39, s4, 0x2000
	s_add_i32 s34, s89, 0xc000
	s_add_u32 s4, s76, 0x84000
	s_addc_u32 s5, s77, 0
	s_mov_b32 m0, s34
	s_nop 0
	global_load_lds_dwordx4 v152, s[4:5]
	s_add_u32 s4, s76, 0x86000
	s_addc_u32 s5, s77, 0
	s_add_i32 s12, s89, 0xe000
	s_mov_b32 m0, s12
	s_nop 0
	global_load_lds_dwordx4 v152, s[4:5]
	s_lshl_b32 s9, s10, 11
	s_cmp_gt_i32 s10, 0
	s_cselect_b64 s[60:61], -1, 0
	s_cmp_gt_i32 s10, -2
	s_cselect_b64 s[64:65], -1, 0
	s_add_i32 s11, s49, s9
	s_cmpk_lt_u32 s1, 0x100
	s_cselect_b64 s[62:63], -1, 0
	s_bfe_u32 s12, s1, 0x10006
	s_lshl_b32 s1, s10, 3
	s_and_b32 s1, s1, 8
	v_cmp_gt_u32_e32 vcc, 2, v153
	s_or_b32 s1, s1, s12
	s_and_b64 s[66:67], s[62:63], vcc
	s_lshl_b32 s13, s1, 10
	s_add_i32 s25, s89, 0xe000
	s_mul_i32 s4, s0, 0xb000
	v_and_b32_e32 v2, 24, v2
	s_mul_hi_i32 s1, s0, 0xb000
	s_add_u32 s10, s30, s4
	s_addc_u32 s1, s48, s1
	v_lshl_or_b32 v155, s8, 5, v2
	v_lshlrev_b32_e32 v5, 10, v153
	s_cmp_eq_u32 s0, 3
	v_lshlrev_b32_e32 v2, 2, v155
	v_add_u32_e32 v6, s9, v5
	v_readlane_b32 s0, v255, 39
	v_readlane_b32 s8, v255, 40
	v_readlane_b32 s30, v255, 41
	v_readlane_b32 s48, v255, 42
	v_or_b32_e32 v5, 0xfffff800, v5
	s_waitcnt vmcnt(8)
	v_add_u32_e32 v3, s49, v2
	v_add_u32_e32 v157, s0, v2
	v_add_u32_e32 v158, s8, v2
	v_add_u32_e32 v159, s30, v2
	v_add_u32_e32 v160, s48, v2
	v_or_b32_e32 v8, 16, v2
	v_add_u32_e32 v9, s11, v5
	v_or_b32_e32 v10, 0x200, v2
	v_or_b32_e32 v2, 0x210, v2
	v_cmp_gt_u32_e32 vcc, 32, v1
	v_add_u32_e32 v6, 0xffffc800, v6
	v_add_u32_e32 v7, s9, v3
	v_add_u32_e32 v161, s0, v8
	v_add_u32_e32 v162, s8, v8
	v_add_u32_e32 v163, s30, v8
	v_add_u32_e32 v164, s48, v8
	v_add_u32_e32 v165, v9, v8
	v_add_u32_e32 v8, s11, v8
	v_add_u32_e32 v166, s0, v10
	v_add_u32_e32 v167, s8, v10
	v_add_u32_e32 v168, s30, v10
	v_add_u32_e32 v169, s48, v10
	v_add_u32_e32 v170, v9, v10
	v_add_u32_e32 v10, s11, v10
	v_add_u32_e32 v171, s0, v2
	v_add_u32_e32 v172, s8, v2
	v_add_u32_e32 v173, s30, v2
	v_add_u32_e32 v174, s48, v2
	v_add_u32_e32 v175, v9, v2
	v_add_u32_e32 v2, s11, v2
	v_cndmask_b32_e64 v1, v254, 0, vcc
	s_movk_i32 s0, 0x1f0
	s_cselect_b32 s30, s7, s1
	s_cselect_b32 s96, s6, s10
	v_readlane_b32 s6, v255, 29
	s_mov_b32 s86, s88
	s_mov_b32 s22, 0
	v_cmp_lt_u32_e64 s[4:5], 13, v153
	v_add_u32_e32 v156, -14, v153
	v_and_or_b32 v176, v152, s0, v1
	v_add_u32_e32 v177, 0, v0
	v_add_u32_e32 v178, 0, v4
	v_add_u32_e32 v179, v3, v6
	v_add_u32_e32 v180, v8, v5
	v_add_u32_e32 v181, v10, v5
	v_add_u32_e32 v182, v2, v5
	v_add_u32_e32 v183, v7, v5
	v_readlane_b32 s1, v255, 22
	s_mov_b32 s88, s6
	s_barrier
	v_readlane_b32 s7, v255, 30
	s_branch .LBB0_735

; #define PG8_STAGE(bufoff, gbase, hoff, imm) do { _Pragma("unroll") for (int _i = 0; _i < 2; ++_i) { \
;         asm volatile("s_mov_b32 m0, %0\n\ts_nop 0\n\tglobal_load_lds_dwordx4 %1, %2" \
;             :: "s"(lds0 + (unsigned)((bufoff) + _i * 8192)), "v"(voff0), "s"((const char*)(gbase) + (size_t)(hoff) + (size_t)(_i * 8192)) : "memory"); } } while (0)
; #define PG8_LDA(dst, b, h) do { _Pragma("unroll") for (int m = 0; m < 4; ++m) _Pragma("unroll") for (int k = 0; k < 2; ++k) dst[m][k] = *(const LAS bf16x8*)(lds + PG8_SA(b, h) + aoff + m * 2048 + k * 1024); } while (0)
; #define PG8_LDB(dst, b, h) do { _Pragma("unroll") for (int n = 0; n < 2; ++n) _Pragma("unroll") for (int k = 0; k < 2; ++k) dst[n][k] = *(const LAS bf16x8*)(lds + PG8_SB(b, h) + boff + n * 2048 + k * 1024); } while (0)
; #define PG8_MMA(ai, bj, At, Bt) do { __builtin_amdgcn_s_setprio(1); _Pragma("unroll") for (int m = 0; m < 4; ++m) _Pragma("unroll") for (int n = 0; n < 2; ++n) _Pragma("unroll") for (int k = 0; k < 2; ++k) \
;         acc[ai][bj][m][n] = __builtin_amdgcn_mfma_f32_16x16x32_bf16(Bt[n][k], At[m][k], acc[ai][bj][m][n], 0, 0, 0); __builtin_amdgcn_s_setprio(0); } while (0)
; #define PG8_WAIT_V(n) asm volatile("s_waitcnt vmcnt(" #n ")" ::: "memory")
; #define PG8_WAIT_L(n) asm volatile("s_waitcnt lgkmcnt(" #n ")" ::: "memory")
; #define PG8_BAR __builtin_amdgcn_s_barrier()
; #define PG8_SCHED __builtin_amdgcn_sched_barrier(0)
; template <class Epi>
; __device__ __forceinline__ void gemm_phase(LAS unsigned char* lds, const Gemm g, const StaticOrder& S, const Epi& E) {
;     ...
;             const char* aT = cA + (size_t)t * KS;
;             const char* a2 = last ? nA : aT + 2 * KS; const char* b2 = last ? nB : cB + (size_t)(t + 2) * KS;
;             PG8_LDB(B0, 0, 0); PG8_SCHED; PG8_LDA(At, 0, 0); PG8_STAGE(PG8_SA(1, 1), aT + KS, hA, 0);
;             PG8_WAIT_L(8); PG8_BAR; PG8_WAIT_L(0); PG8_MMA(0, 0, At, B0); PG8_BAR; PG8_SCHED;
;             PG8_LDB(B1, 0, 1); PG8_STAGE(PG8_SB(0, 0), b2, 0, 0);
;             PG8_BAR; PG8_WAIT_L(0); PG8_MMA(0, 1, At, B1); PG8_BAR;
;             PG8_LDA(At, 0, 1); PG8_STAGE(PG8_SA(0, 0), a2, 0, 0);
;             PG8_BAR; PG8_WAIT_L(0); PG8_MMA(1, 0, At, B0); PG8_BAR; PG8_SCHED;
;             PG8_STAGE(PG8_SB(0, 1), b2, hB, 0);
;             PG8_WAIT_V(6); PG8_BAR; PG8_MMA(1, 1, At, B1); PG8_BAR;
.LBB0_738:
	v_add_u32_e32 v140, 0x10000, v177
	ds_read_b128 v[128:131], v140
	ds_read_b128 v[132:135], v140 offset:1024
	ds_read_b128 v[136:139], v140 offset:2048
	ds_read_b128 v[140:143], v140 offset:3072
	s_add_u32 s78, s76, 0x8000
	s_addc_u32 s79, s77, 0
	s_and_b64 s[48:49], s[82:83], exec
	s_cselect_b32 s81, s50, s79
	s_cselect_b32 s80, s51, s78
	ds_read_b128 v[144:147], v178
	ds_read_b128 v[148:151], v178 offset:1024
	ds_read_b128 v[184:187], v178 offset:2048
	ds_read_b128 v[200:203], v178 offset:3072
	ds_read_b128 v[204:207], v178 offset:4096
	ds_read_b128 v[208:211], v178 offset:5120
	ds_read_b128 v[212:215], v178 offset:6144
	ds_read_b128 v[236:239], v178 offset:7168
	s_waitcnt lgkmcnt(8)
	s_waitcnt vmcnt(10)
	s_barrier
	s_waitcnt lgkmcnt(0)
	s_waitcnt lgkmcnt(7)
	v_mfma_f32_16x16x32_bf16 v[116:119], v[128:131], v[144:147], v[116:119]
	v_mfma_f32_16x16x32_bf16 v[80:83], v[136:139], v[144:147], v[80:83]
	s_waitcnt lgkmcnt(5)
	v_mfma_f32_16x16x32_bf16 v[88:91], v[128:131], v[184:187], v[88:91]
	v_mfma_f32_16x16x32_bf16 v[84:87], v[136:139], v[184:187], v[84:87]
	s_waitcnt lgkmcnt(3)
	v_mfma_f32_16x16x32_bf16 v[120:123], v[128:131], v[204:207], v[120:123]
	v_mfma_f32_16x16x32_bf16 v[92:95], v[136:139], v[204:207], v[92:95]
	s_waitcnt lgkmcnt(1)
	v_mfma_f32_16x16x32_bf16 v[124:127], v[128:131], v[212:215], v[124:127]
	v_mfma_f32_16x16x32_bf16 v[96:99], v[136:139], v[212:215], v[96:99]
	v_mfma_f32_16x16x32_bf16 v[116:119], v[132:135], v[148:151], v[116:119]
	v_mfma_f32_16x16x32_bf16 v[80:83], v[140:143], v[148:151], v[80:83]
	v_mfma_f32_16x16x32_bf16 v[88:91], v[132:135], v[200:203], v[88:91]
	v_mfma_f32_16x16x32_bf16 v[84:87], v[140:143], v[200:203], v[84:87]
	v_mfma_f32_16x16x32_bf16 v[120:123], v[132:135], v[208:211], v[120:123]
	v_mfma_f32_16x16x32_bf16 v[92:95], v[140:143], v[208:211], v[92:95]
	s_waitcnt lgkmcnt(0)
	v_mfma_f32_16x16x32_bf16 v[124:127], v[132:135], v[236:239], v[124:127]
	v_mfma_f32_16x16x32_bf16 v[96:99], v[140:143], v[236:239], v[96:99]
	s_barrier
	v_add_u32_e32 v188, 0x14000, v177
	ds_read_b128 v[240:243], v188
	ds_read_b128 v[244:247], v188 offset:1024
	ds_read_b128 v[248:251], v188 offset:2048
	ds_read_b128 v[230:233], v188 offset:3072
	s_and_b64 s[48:49], s[82:83], exec
	s_cselect_b32 s76, s0, s1
	s_cselect_b32 s77, s69, s9
	s_mov_b32 m0, s28
	s_nop 0
	global_load_lds_dwordx4 v152, s[76:77]
	s_add_u32 s48, s76, 0x2000
	s_addc_u32 s49, s77, 0
	s_mov_b32 m0, s29
	s_nop 0
	global_load_lds_dwordx4 v152, s[48:49]
	s_waitcnt vmcnt(10)
	s_barrier
	s_waitcnt lgkmcnt(0)
	s_waitcnt lgkmcnt(3)
	v_mfma_f32_16x16x32_bf16 v[48:51], v[240:243], v[144:147], v[48:51]
	s_waitcnt lgkmcnt(1)
	v_mfma_f32_16x16x32_bf16 v[16:19], v[248:251], v[144:147], v[16:19]
	v_mfma_f32_16x16x32_bf16 v[52:55], v[240:243], v[184:187], v[52:55]
	v_mfma_f32_16x16x32_bf16 v[20:23], v[248:251], v[184:187], v[20:23]
	v_mfma_f32_16x16x32_bf16 v[56:59], v[240:243], v[204:207], v[56:59]
	v_mfma_f32_16x16x32_bf16 v[24:27], v[248:251], v[204:207], v[24:27]
	v_mfma_f32_16x16x32_bf16 v[60:63], v[240:243], v[212:215], v[60:63]
	v_mfma_f32_16x16x32_bf16 v[28:31], v[248:251], v[212:215], v[28:31]
	v_mfma_f32_16x16x32_bf16 v[48:51], v[244:247], v[148:151], v[48:51]
	s_waitcnt lgkmcnt(0)
	v_mfma_f32_16x16x32_bf16 v[16:19], v[230:233], v[148:151], v[16:19]
	v_mfma_f32_16x16x32_bf16 v[52:55], v[244:247], v[200:203], v[52:55]
	v_mfma_f32_16x16x32_bf16 v[20:23], v[230:233], v[200:203], v[20:23]
	v_mfma_f32_16x16x32_bf16 v[56:59], v[244:247], v[208:211], v[56:59]
	v_mfma_f32_16x16x32_bf16 v[24:27], v[230:233], v[208:211], v[24:27]
	v_mfma_f32_16x16x32_bf16 v[60:63], v[244:247], v[236:239], v[60:63]
	v_mfma_f32_16x16x32_bf16 v[28:31], v[230:233], v[236:239], v[28:31]
	s_barrier
	ds_read_b128 v[144:147], v178 offset:16384
	ds_read_b128 v[148:151], v178 offset:17408
	ds_read_b128 v[184:187], v178 offset:18432
	ds_read_b128 v[200:203], v178 offset:19456
	ds_read_b128 v[204:207], v178 offset:20480
	ds_read_b128 v[208:211], v178 offset:21504
	ds_read_b128 v[212:215], v178 offset:22528
	ds_read_b128 v[236:239], v178 offset:23552
	s_mov_b32 m0, s89
	s_nop 0
	global_load_lds_dwordx4 v152, s[80:81]
	s_add_u32 s48, s80, 0x2000
	s_addc_u32 s49, s81, 0
	s_mov_b32 m0, s40
	s_nop 0
	global_load_lds_dwordx4 v152, s[48:49]
	s_barrier
	s_waitcnt lgkmcnt(0)
	s_waitcnt lgkmcnt(7)
	v_mfma_f32_16x16x32_bf16 v[100:103], v[128:131], v[144:147], v[100:103]
	v_mfma_f32_16x16x32_bf16 v[64:67], v[136:139], v[144:147], v[64:67]
	s_waitcnt lgkmcnt(5)
	v_mfma_f32_16x16x32_bf16 v[104:107], v[128:131], v[184:187], v[104:107]
	v_mfma_f32_16x16x32_bf16 v[68:71], v[136:139], v[184:187], v[68:71]
	s_waitcnt lgkmcnt(3)
	v_mfma_f32_16x16x32_bf16 v[108:111], v[128:131], v[204:207], v[108:111]
	v_mfma_f32_16x16x32_bf16 v[72:75], v[136:139], v[204:207], v[72:75]
	s_waitcnt lgkmcnt(1)
	v_mfma_f32_16x16x32_bf16 v[112:115], v[128:131], v[212:215], v[112:115]
	v_mfma_f32_16x16x32_bf16 v[76:79], v[136:139], v[212:215], v[76:79]
	v_mfma_f32_16x16x32_bf16 v[100:103], v[132:135], v[148:151], v[100:103]
	v_mfma_f32_16x16x32_bf16 v[64:67], v[140:143], v[148:151], v[64:67]
	v_mfma_f32_16x16x32_bf16 v[104:107], v[132:135], v[200:203], v[104:107]
	v_mfma_f32_16x16x32_bf16 v[68:71], v[140:143], v[200:203], v[68:71]
	v_mfma_f32_16x16x32_bf16 v[108:111], v[132:135], v[208:211], v[108:111]
	v_mfma_f32_16x16x32_bf16 v[72:75], v[140:143], v[208:211], v[72:75]
	s_waitcnt lgkmcnt(0)
	v_mfma_f32_16x16x32_bf16 v[112:115], v[132:135], v[236:239], v[112:115]
	v_mfma_f32_16x16x32_bf16 v[76:79], v[140:143], v[236:239], v[76:79]
	s_barrier
; #define PG8_STAGE(bufoff, gbase, hoff, imm) do { _Pragma("unroll") for (int _i = 0; _i < 2; ++_i) { \
;         asm volatile("s_mov_b32 m0, %0\n\ts_nop 0\n\tglobal_load_lds_dwordx4 %1, %2" \
;             :: "s"(lds0 + (unsigned)((bufoff) + _i * 8192)), "v"(voff0), "s"((const char*)(gbase) + (size_t)(hoff) + (size_t)(_i * 8192)) : "memory"); } } while (0)
; #define PG8_LDA(dst, b, h) do { _Pragma("unroll") for (int m = 0; m < 4; ++m) _Pragma("unroll") for (int k = 0; k < 2; ++k) dst[m][k] = *(const LAS bf16x8*)(lds + PG8_SA(b, h) + aoff + m * 2048 + k * 1024); } while (0)
; #define PG8_LDB(dst, b, h) do { _Pragma("unroll") for (int n = 0; n < 2; ++n) _Pragma("unroll") for (int k = 0; k < 2; ++k) dst[n][k] = *(const LAS bf16x8*)(lds + PG8_SB(b, h) + boff + n * 2048 + k * 1024); } while (0)
; #define PG8_MMA(ai, bj, At, Bt) do { __builtin_amdgcn_s_setprio(1); _Pragma("unroll") for (int m = 0; m < 4; ++m) _Pragma("unroll") for (int n = 0; n < 2; ++n) _Pragma("unroll") for (int k = 0; k < 2; ++k) \
;         acc[ai][bj][m][n] = __builtin_amdgcn_mfma_f32_16x16x32_bf16(Bt[n][k], At[m][k], acc[ai][bj][m][n], 0, 0, 0); __builtin_amdgcn_s_setprio(0); } while (0)
; #define PG8_WAIT_V(n) asm volatile("s_waitcnt vmcnt(" #n ")" ::: "memory")
; #define PG8_WAIT_L(n) asm volatile("s_waitcnt lgkmcnt(" #n ")" ::: "memory")
; #define PG8_BAR __builtin_amdgcn_s_barrier()
; #define PG8_SCHED __builtin_amdgcn_sched_barrier(0)
; template <class Epi>
; __device__ __forceinline__ void gemm_phase(LAS unsigned char* lds, const Gemm g, const StaticOrder& S, const Epi& E) {
;     ...
;             PG8_STAGE(PG8_SB(0, 1), b2, hB, 0);
;             PG8_WAIT_V(6); PG8_BAR; PG8_MMA(1, 1, At, B1); PG8_BAR;
;             PG8_LDB(B0, 1, 0); PG8_SCHED; PG8_LDA(At, 1, 0); PG8_STAGE(PG8_SA(0, 1), a2, hA, 0);
;             PG8_WAIT_L(8); PG8_BAR; PG8_WAIT_L(0); PG8_MMA(0, 0, At, B0); PG8_BAR; PG8_SCHED;
;             PG8_LDB(B1, 1, 1); PG8_STAGE(PG8_SB(1, 0), b2 + KS, 0, 0);
	s_add_u32 s48, s76, 0x80000
	s_addc_u32 s49, s77, 0
	s_mov_b32 m0, s41
	s_nop 0
	global_load_lds_dwordx4 v152, s[48:49]
	s_add_u32 s48, s76, 0x82000
	s_addc_u32 s49, s77, 0
	s_mov_b32 m0, s42
	s_nop 0
	global_load_lds_dwordx4 v152, s[48:49]
	s_add_u32 s48, s80, 0x80000
	s_addc_u32 s49, s81, 0
	s_mov_b32 m0, s43
	s_nop 0
	global_load_lds_dwordx4 v152, s[48:49]
	s_add_u32 s48, s80, 0x82000
	s_addc_u32 s49, s81, 0
	s_mov_b32 m0, s92
	s_nop 0
	global_load_lds_dwordx4 v152, s[48:49]
	s_waitcnt vmcnt(12)
	s_barrier
	v_mfma_f32_16x16x32_bf16 v[32:35], v[240:243], v[144:147], v[32:35]
	v_mfma_f32_16x16x32_bf16 v[0:3], v[248:251], v[144:147], v[0:3]
	v_mfma_f32_16x16x32_bf16 v[36:39], v[240:243], v[184:187], v[36:39]
	v_mfma_f32_16x16x32_bf16 v[4:7], v[248:251], v[184:187], v[4:7]
	v_mfma_f32_16x16x32_bf16 v[40:43], v[240:243], v[204:207], v[40:43]
	v_mfma_f32_16x16x32_bf16 v[8:11], v[248:251], v[204:207], v[8:11]
	v_mfma_f32_16x16x32_bf16 v[44:47], v[240:243], v[212:215], v[44:47]
	v_mfma_f32_16x16x32_bf16 v[12:15], v[248:251], v[212:215], v[12:15]
	v_mfma_f32_16x16x32_bf16 v[32:35], v[244:247], v[148:151], v[32:35]
	v_mfma_f32_16x16x32_bf16 v[0:3], v[230:233], v[148:151], v[0:3]
	v_mfma_f32_16x16x32_bf16 v[36:39], v[244:247], v[200:203], v[36:39]
	v_mfma_f32_16x16x32_bf16 v[4:7], v[230:233], v[200:203], v[4:7]
	v_mfma_f32_16x16x32_bf16 v[40:43], v[244:247], v[208:211], v[40:43]
	v_mfma_f32_16x16x32_bf16 v[8:11], v[230:233], v[208:211], v[8:11]
	v_mfma_f32_16x16x32_bf16 v[44:47], v[244:247], v[236:239], v[44:47]
	v_mfma_f32_16x16x32_bf16 v[12:15], v[230:233], v[236:239], v[12:15]
	v_add_u32_e32 v140, 0x18000, v177
	s_barrier
	ds_read_b128 v[128:131], v140
	ds_read_b128 v[132:135], v140 offset:1024
	ds_read_b128 v[136:139], v140 offset:2048
	ds_read_b128 v[140:143], v140 offset:3072
	ds_read_b128 v[144:147], v178 offset:32768
	ds_read_b128 v[148:151], v178 offset:33792
	ds_read_b128 v[184:187], v178 offset:34816
	ds_read_b128 v[200:203], v178 offset:35840
	ds_read_b128 v[204:207], v178 offset:36864
	ds_read_b128 v[208:211], v178 offset:37888
	ds_read_b128 v[212:215], v178 offset:38912
	ds_read_b128 v[230:233], v178 offset:39936
	s_waitcnt lgkmcnt(8)
	s_waitcnt vmcnt(10)
	s_barrier
	s_waitcnt lgkmcnt(0)
	s_waitcnt lgkmcnt(7)
	v_mfma_f32_16x16x32_bf16 v[116:119], v[128:131], v[144:147], v[116:119]
	v_mfma_f32_16x16x32_bf16 v[80:83], v[136:139], v[144:147], v[80:83]
	s_waitcnt lgkmcnt(5)
	v_mfma_f32_16x16x32_bf16 v[88:91], v[128:131], v[184:187], v[88:91]
	v_mfma_f32_16x16x32_bf16 v[84:87], v[136:139], v[184:187], v[84:87]
	s_waitcnt lgkmcnt(3)
	v_mfma_f32_16x16x32_bf16 v[120:123], v[128:131], v[204:207], v[120:123]
	v_mfma_f32_16x16x32_bf16 v[92:95], v[136:139], v[204:207], v[92:95]
	s_waitcnt lgkmcnt(1)
	v_mfma_f32_16x16x32_bf16 v[124:127], v[128:131], v[212:215], v[124:127]
	v_mfma_f32_16x16x32_bf16 v[96:99], v[136:139], v[212:215], v[96:99]
	v_mfma_f32_16x16x32_bf16 v[116:119], v[132:135], v[148:151], v[116:119]
	v_mfma_f32_16x16x32_bf16 v[80:83], v[140:143], v[148:151], v[80:83]
	v_mfma_f32_16x16x32_bf16 v[88:91], v[132:135], v[200:203], v[88:91]
	v_mfma_f32_16x16x32_bf16 v[84:87], v[140:143], v[200:203], v[84:87]
	v_mfma_f32_16x16x32_bf16 v[120:123], v[132:135], v[208:211], v[120:123]
	v_mfma_f32_16x16x32_bf16 v[92:95], v[140:143], v[208:211], v[92:95]
	s_waitcnt lgkmcnt(0)
	v_mfma_f32_16x16x32_bf16 v[124:127], v[132:135], v[230:233], v[124:127]
	v_mfma_f32_16x16x32_bf16 v[96:99], v[140:143], v[230:233], v[96:99]
	s_barrier
	v_add_u32_e32 v188, 0x1c000, v177
	ds_read_b128 v[236:239], v188
	ds_read_b128 v[240:243], v188 offset:1024
	ds_read_b128 v[244:247], v188 offset:2048
	ds_read_b128 v[248:251], v188 offset:3072
	s_add_u32 s48, s76, 0x4000
	s_addc_u32 s49, s77, 0
	s_mov_b32 m0, s16
	s_nop 0
	global_load_lds_dwordx4 v152, s[48:49]
	s_add_u32 s48, s76, 0x6000
	s_addc_u32 s49, s77, 0
	s_mov_b32 m0, s17
	s_nop 0
	global_load_lds_dwordx4 v152, s[48:49]
	s_waitcnt vmcnt(10)
	s_barrier
; #define PG8_STAGE(bufoff, gbase, hoff, imm) do { _Pragma("unroll") for (int _i = 0; _i < 2; ++_i) { \
;         asm volatile("s_mov_b32 m0, %0\n\ts_nop 0\n\tglobal_load_lds_dwordx4 %1, %2" \
;             :: "s"(lds0 + (unsigned)((bufoff) + _i * 8192)), "v"(voff0), "s"((const char*)(gbase) + (size_t)(hoff) + (size_t)(_i * 8192)) : "memory"); } } while (0)
; #define PG8_LDA(dst, b, h) do { _Pragma("unroll") for (int m = 0; m < 4; ++m) _Pragma("unroll") for (int k = 0; k < 2; ++k) dst[m][k] = *(const LAS bf16x8*)(lds + PG8_SA(b, h) + aoff + m * 2048 + k * 1024); } while (0)
; #define PG8_LDB(dst, b, h) do { _Pragma("unroll") for (int n = 0; n < 2; ++n) _Pragma("unroll") for (int k = 0; k < 2; ++k) dst[n][k] = *(const LAS bf16x8*)(lds + PG8_SB(b, h) + boff + n * 2048 + k * 1024); } while (0)
; #define PG8_MMA(ai, bj, At, Bt) do { __builtin_amdgcn_s_setprio(1); _Pragma("unroll") for (int m = 0; m < 4; ++m) _Pragma("unroll") for (int n = 0; n < 2; ++n) _Pragma("unroll") for (int k = 0; k < 2; ++k) \
;         acc[ai][bj][m][n] = __builtin_amdgcn_mfma_f32_16x16x32_bf16(Bt[n][k], At[m][k], acc[ai][bj][m][n], 0, 0, 0); __builtin_amdgcn_s_setprio(0); } while (0)
; #define PG8_WAIT_V(n) asm volatile("s_waitcnt vmcnt(" #n ")" ::: "memory")
; #define PG8_WAIT_L(n) asm volatile("s_waitcnt lgkmcnt(" #n ")" ::: "memory")
; #define PG8_BAR __builtin_amdgcn_s_barrier()
; #define PG8_SCHED __builtin_amdgcn_sched_barrier(0)
; template <class Epi>
; __device__ __forceinline__ void gemm_phase(LAS unsigned char* lds, const Gemm g, const StaticOrder& S, const Epi& E) {
;     ...
;             PG8_LDB(B1, 1, 1); PG8_STAGE(PG8_SB(1, 0), b2 + KS, 0, 0);
;             PG8_BAR; PG8_WAIT_L(0); PG8_MMA(0, 1, At, B1); PG8_BAR;
;             PG8_LDA(At, 1, 1); PG8_STAGE(PG8_SA(1, 0), a2 + KS, 0, 0);
;             PG8_BAR; PG8_WAIT_L(0); PG8_MMA(1, 0, At, B0); PG8_BAR; PG8_SCHED;
;             PG8_STAGE(PG8_SB(1, 1), b2 + KS, hB, 0);
;             PG8_WAIT_V(6); PG8_BAR; PG8_MMA(1, 1, At, B1); PG8_BAR;
;         }
	s_waitcnt lgkmcnt(0)
	s_waitcnt lgkmcnt(3)
	v_mfma_f32_16x16x32_bf16 v[48:51], v[236:239], v[144:147], v[48:51]
	s_waitcnt lgkmcnt(1)
	v_mfma_f32_16x16x32_bf16 v[16:19], v[244:247], v[144:147], v[16:19]
	v_mfma_f32_16x16x32_bf16 v[52:55], v[236:239], v[184:187], v[52:55]
	v_mfma_f32_16x16x32_bf16 v[20:23], v[244:247], v[184:187], v[20:23]
	v_mfma_f32_16x16x32_bf16 v[56:59], v[236:239], v[204:207], v[56:59]
	v_mfma_f32_16x16x32_bf16 v[24:27], v[244:247], v[204:207], v[24:27]
	v_mfma_f32_16x16x32_bf16 v[60:63], v[236:239], v[212:215], v[60:63]
	v_mfma_f32_16x16x32_bf16 v[28:31], v[244:247], v[212:215], v[28:31]
	v_mfma_f32_16x16x32_bf16 v[48:51], v[240:243], v[148:151], v[48:51]
	s_waitcnt lgkmcnt(0)
	v_mfma_f32_16x16x32_bf16 v[16:19], v[248:251], v[148:151], v[16:19]
	v_mfma_f32_16x16x32_bf16 v[52:55], v[240:243], v[200:203], v[52:55]
	v_mfma_f32_16x16x32_bf16 v[20:23], v[248:251], v[200:203], v[20:23]
	v_mfma_f32_16x16x32_bf16 v[56:59], v[240:243], v[208:211], v[56:59]
	v_mfma_f32_16x16x32_bf16 v[24:27], v[248:251], v[208:211], v[24:27]
	v_mfma_f32_16x16x32_bf16 v[60:63], v[240:243], v[230:233], v[60:63]
	v_mfma_f32_16x16x32_bf16 v[28:31], v[248:251], v[230:233], v[28:31]
	s_barrier
	ds_read_b128 v[144:147], v178 offset:49152
	ds_read_b128 v[148:151], v178 offset:50176
	ds_read_b128 v[184:187], v178 offset:51200
	ds_read_b128 v[200:203], v178 offset:52224
	ds_read_b128 v[204:207], v178 offset:53248
	ds_read_b128 v[208:211], v178 offset:54272
	ds_read_b128 v[212:215], v178 offset:55296
	ds_read_b128 v[230:233], v178 offset:56320
	s_add_u32 s48, s80, 0x4000
	s_addc_u32 s49, s81, 0
	s_mov_b32 m0, s24
	s_nop 0
	global_load_lds_dwordx4 v152, s[48:49]
	s_add_u32 s48, s80, 0x6000
	s_addc_u32 s49, s81, 0
	s_mov_b32 m0, s37
	s_nop 0
	global_load_lds_dwordx4 v152, s[48:49]
	s_barrier
	s_waitcnt lgkmcnt(0)
	s_waitcnt lgkmcnt(7)
	v_mfma_f32_16x16x32_bf16 v[100:103], v[128:131], v[144:147], v[100:103]
	v_mfma_f32_16x16x32_bf16 v[64:67], v[136:139], v[144:147], v[64:67]
	s_waitcnt lgkmcnt(5)
	v_mfma_f32_16x16x32_bf16 v[104:107], v[128:131], v[184:187], v[104:107]
	v_mfma_f32_16x16x32_bf16 v[68:71], v[136:139], v[184:187], v[68:71]
	s_waitcnt lgkmcnt(3)
	v_mfma_f32_16x16x32_bf16 v[108:111], v[128:131], v[204:207], v[108:111]
	v_mfma_f32_16x16x32_bf16 v[72:75], v[136:139], v[204:207], v[72:75]
	s_waitcnt lgkmcnt(1)
	v_mfma_f32_16x16x32_bf16 v[112:115], v[128:131], v[212:215], v[112:115]
	v_mfma_f32_16x16x32_bf16 v[76:79], v[136:139], v[212:215], v[76:79]
	v_mfma_f32_16x16x32_bf16 v[100:103], v[132:135], v[148:151], v[100:103]
	v_mfma_f32_16x16x32_bf16 v[64:67], v[140:143], v[148:151], v[64:67]
	v_mfma_f32_16x16x32_bf16 v[104:107], v[132:135], v[200:203], v[104:107]
	v_mfma_f32_16x16x32_bf16 v[68:71], v[140:143], v[200:203], v[68:71]
	v_mfma_f32_16x16x32_bf16 v[108:111], v[132:135], v[208:211], v[108:111]
	v_mfma_f32_16x16x32_bf16 v[72:75], v[140:143], v[208:211], v[72:75]
	s_waitcnt lgkmcnt(0)
	v_mfma_f32_16x16x32_bf16 v[112:115], v[132:135], v[230:233], v[112:115]
	v_mfma_f32_16x16x32_bf16 v[76:79], v[140:143], v[230:233], v[76:79]
	s_barrier
	s_add_u32 s48, s76, 0x84000
	s_addc_u32 s49, s77, 0
	s_mov_b32 m0, s97
	s_nop 0
	global_load_lds_dwordx4 v152, s[48:49]
	s_add_u32 s48, s76, 0x86000
	s_addc_u32 s49, s77, 0
	s_mov_b32 m0, s38
	s_nop 0
	global_load_lds_dwordx4 v152, s[48:49]
	s_add_u32 s48, s80, 0x84000
	s_addc_u32 s49, s81, 0
	s_mov_b32 m0, s34
	s_nop 0
	global_load_lds_dwordx4 v152, s[48:49]
	s_add_u32 s48, s80, 0x86000
	s_addc_u32 s49, s81, 0
	s_mov_b32 m0, s25
	s_nop 0
	global_load_lds_dwordx4 v152, s[48:49]
	s_waitcnt vmcnt(12)
	s_barrier
	v_mfma_f32_16x16x32_bf16 v[32:35], v[236:239], v[144:147], v[32:35]
	v_mfma_f32_16x16x32_bf16 v[0:3], v[244:247], v[144:147], v[0:3]
	v_mfma_f32_16x16x32_bf16 v[36:39], v[236:239], v[184:187], v[36:39]
	v_mfma_f32_16x16x32_bf16 v[4:7], v[244:247], v[184:187], v[4:7]
	v_mfma_f32_16x16x32_bf16 v[40:43], v[236:239], v[204:207], v[40:43]
	v_mfma_f32_16x16x32_bf16 v[8:11], v[244:247], v[204:207], v[8:11]
	v_mfma_f32_16x16x32_bf16 v[44:47], v[236:239], v[212:215], v[44:47]
	v_mfma_f32_16x16x32_bf16 v[12:15], v[244:247], v[212:215], v[12:15]
	v_mfma_f32_16x16x32_bf16 v[32:35], v[240:243], v[148:151], v[32:35]
	v_mfma_f32_16x16x32_bf16 v[0:3], v[248:251], v[148:151], v[0:3]
	v_mfma_f32_16x16x32_bf16 v[36:39], v[240:243], v[200:203], v[36:39]
	v_mfma_f32_16x16x32_bf16 v[4:7], v[248:251], v[200:203], v[4:7]
	v_mfma_f32_16x16x32_bf16 v[40:43], v[240:243], v[208:211], v[40:43]
	v_mfma_f32_16x16x32_bf16 v[8:11], v[248:251], v[208:211], v[8:11]
	v_mfma_f32_16x16x32_bf16 v[44:47], v[240:243], v[230:233], v[44:47]
	v_mfma_f32_16x16x32_bf16 v[12:15], v[248:251], v[230:233], v[12:15]
	s_add_i32 s71, s71, 2
	s_add_u32 s1, s1, 0x8000
	s_addc_u32 s9, s9, 0
	s_cmp_gt_u32 s71, 29
	s_mov_b64 s[76:77], s[78:79]
	s_barrier
	s_cbranch_scc1 .LBB0_741
